# adds: shift-times-weight phase fetches both weight rows of a pass together (half the dependent round trips); drops the silu(c) unroll
# speedup vs baseline: 1.0497x; 1.0043x over previous
.LBB0_161:
	s_waitcnt lgkmcnt(0)
	global_load_dwordx4 v[90:93], v[76:77], off offset:-2032
	global_load_dwordx4 v[94:97], v[76:77], off offset:-2048
	global_load_dwordx4 v[128:131], v[76:77], off offset:16
	global_load_dwordx4 v[132:135], v[76:77], off
	s_waitcnt vmcnt(0)
	v_lshlrev_b32_e32 v106, 16, v92
	v_lshlrev_b32_e32 v100, 16, v96
	v_and_b32_e32 v101, 0xffff0000, v96
	v_lshlrev_b32_e32 v96, 16, v97
	v_and_b32_e32 v97, 0xffff0000, v97
	v_and_b32_e32 v107, 0xffff0000, v92
	v_lshlrev_b32_e32 v108, 16, v93
	v_and_b32_e32 v109, 0xffff0000, v93
	v_lshlrev_b32_e32 v78, 16, v94
	v_and_b32_e32 v79, 0xffff0000, v94
	v_lshlrev_b32_e32 v98, 16, v95
	v_and_b32_e32 v99, 0xffff0000, v95
	v_lshlrev_b32_e32 v102, 16, v90
	v_and_b32_e32 v103, 0xffff0000, v90
	v_lshlrev_b32_e32 v104, 16, v91
	v_and_b32_e32 v105, 0xffff0000, v91
	v_pk_mul_f32 v[90:91], v[10:11], v[96:97]
	v_pk_mul_f32 v[92:93], v[8:9], v[100:101]
	v_pk_mul_f32 v[94:95], v[2:3], v[108:109]
	v_pk_mul_f32 v[110:111], v[0:1], v[106:107]
	v_pk_fma_f32 v[92:93], v[12:13], v[78:79], v[92:93]
	v_pk_fma_f32 v[90:91], v[14:15], v[98:99], v[90:91]
	v_pk_fma_f32 v[110:111], v[4:5], v[102:103], v[110:111]
	v_pk_fma_f32 v[94:95], v[6:7], v[104:105], v[94:95]
	v_pk_add_f32 v[92:93], v[92:93], v[110:111]
	v_pk_add_f32 v[90:91], v[90:91], v[94:95]
	v_pk_mul_f32 v[94:95], v[28:29], v[100:101]
	v_pk_mul_f32 v[112:113], v[20:21], v[106:107]
	v_add_f32_e32 v64, v92, v93
	v_pk_mul_f32 v[92:93], v[30:31], v[96:97]
	v_pk_fma_f32 v[94:95], v[16:17], v[78:79], v[94:95]
	v_pk_mul_f32 v[110:111], v[22:23], v[108:109]
	v_pk_fma_f32 v[112:113], v[24:25], v[102:103], v[112:113]
	v_pk_fma_f32 v[92:93], v[18:19], v[98:99], v[92:93]
	v_pk_fma_f32 v[110:111], v[26:27], v[104:105], v[110:111]
	v_pk_add_f32 v[94:95], v[94:95], v[112:113]
	v_add_f32_e32 v90, v90, v91
	v_pk_add_f32 v[92:93], v[92:93], v[110:111]
	v_add_f32_e32 v91, v94, v95
	v_pk_mul_f32 v[94:95], v[46:47], v[96:97]
	v_pk_mul_f32 v[110:111], v[44:45], v[100:101]
	v_pk_mul_f32 v[96:97], v[62:63], v[96:97]
	v_pk_mul_f32 v[100:101], v[60:61], v[100:101]
	v_pk_fma_f32 v[110:111], v[32:33], v[78:79], v[110:111]
	v_pk_fma_f32 v[94:95], v[34:35], v[98:99], v[94:95]
	v_pk_mul_f32 v[112:113], v[38:39], v[108:109]
	v_pk_mul_f32 v[114:115], v[36:37], v[106:107]
	v_pk_fma_f32 v[78:79], v[48:49], v[78:79], v[100:101]
	v_pk_fma_f32 v[96:97], v[50:51], v[98:99], v[96:97]
	v_pk_mul_f32 v[98:99], v[54:55], v[108:109]
	v_pk_mul_f32 v[100:101], v[52:53], v[106:107]
	v_pk_fma_f32 v[114:115], v[40:41], v[102:103], v[114:115]
	v_pk_fma_f32 v[112:113], v[42:43], v[104:105], v[112:113]
	v_pk_fma_f32 v[100:101], v[56:57], v[102:103], v[100:101]
	v_pk_fma_f32 v[98:99], v[58:59], v[104:105], v[98:99]
	v_pk_add_f32 v[94:95], v[94:95], v[112:113]
	v_pk_add_f32 v[110:111], v[110:111], v[114:115]
	v_pk_add_f32 v[96:97], v[96:97], v[98:99]
	v_pk_add_f32 v[78:79], v[78:79], v[100:101]
	v_add_f32_e32 v92, v92, v93
	v_add_f32_e32 v93, v110, v111
	v_add_f32_e32 v94, v94, v95
	v_add_f32_e32 v78, v78, v79
	v_add_f32_e32 v79, v96, v97
	v_add_f32_e32 v64, v64, v90
	v_add_f32_e32 v91, v91, v92
	v_add_f32_e32 v93, v93, v94
	v_add_f32_e32 v78, v78, v79
	ds_bpermute_b32 v90, v82, v64
	ds_bpermute_b32 v92, v82, v91
	ds_bpermute_b32 v94, v82, v93
	ds_bpermute_b32 v79, v82, v78
	s_waitcnt lgkmcnt(3)
	v_add_f32_e32 v64, v64, v90
	s_waitcnt lgkmcnt(2)
	v_add_f32_e32 v91, v91, v92
	s_waitcnt lgkmcnt(1)
	v_add_f32_e32 v93, v93, v94
	s_waitcnt lgkmcnt(0)
	v_add_f32_e32 v78, v78, v79
	ds_bpermute_b32 v90, v83, v64
	ds_bpermute_b32 v92, v83, v91
	ds_bpermute_b32 v94, v83, v93
	ds_bpermute_b32 v79, v83, v78
	s_waitcnt lgkmcnt(3)
	v_add_f32_e32 v64, v64, v90
	s_waitcnt lgkmcnt(2)
	v_add_f32_e32 v91, v91, v92
	s_waitcnt lgkmcnt(1)
	v_add_f32_e32 v93, v93, v94
	s_waitcnt lgkmcnt(0)
	v_add_f32_e32 v78, v78, v79
	ds_bpermute_b32 v90, v84, v64
	ds_bpermute_b32 v92, v84, v91
	ds_bpermute_b32 v94, v84, v93
	ds_bpermute_b32 v79, v84, v78
	s_waitcnt lgkmcnt(3)
	v_add_f32_e32 v64, v64, v90
	s_waitcnt lgkmcnt(2)
	v_add_f32_e32 v91, v91, v92
	s_waitcnt lgkmcnt(1)
	v_add_f32_e32 v93, v93, v94
	s_waitcnt lgkmcnt(0)
	v_add_f32_e32 v78, v78, v79
	ds_bpermute_b32 v90, v85, v64
	ds_bpermute_b32 v92, v85, v91
	ds_bpermute_b32 v94, v85, v93
	ds_bpermute_b32 v79, v85, v78
	s_waitcnt lgkmcnt(3)
	v_add_f32_e32 v64, v64, v90
	s_waitcnt lgkmcnt(2)
	v_add_f32_e32 v91, v91, v92
	s_waitcnt lgkmcnt(1)
	v_add_f32_e32 v93, v93, v94
	s_waitcnt lgkmcnt(0)
	v_add_f32_e32 v78, v78, v79
	ds_bpermute_b32 v90, v86, v64
	ds_bpermute_b32 v92, v86, v91
	ds_bpermute_b32 v94, v86, v93
	ds_bpermute_b32 v79, v86, v78
	s_waitcnt lgkmcnt(3)
	v_add_f32_e32 v64, v64, v90
	s_waitcnt lgkmcnt(2)
	v_add_f32_e32 v91, v91, v92
	s_waitcnt lgkmcnt(1)
	v_add_f32_e32 v93, v93, v94
	s_waitcnt lgkmcnt(0)
	v_add_f32_e32 v95, v78, v79
	ds_bpermute_b32 v90, v87, v64
	ds_bpermute_b32 v92, v87, v91
	ds_bpermute_b32 v94, v87, v93
	ds_bpermute_b32 v96, v87, v95
	v_lshl_add_u64 v[78:79], v[74:75], 0, s[48:49]
	s_and_saveexec_b64 s[50:51], s[0:1]
	s_cbranch_execz .LBB0_163
	s_waitcnt lgkmcnt(3)
	v_add_f32_e32 v64, v64, v90
	s_waitcnt lgkmcnt(2)
	v_add_f32_e32 v91, v91, v92
	v_cndmask_b32_e64 v64, 0, v64, s[4:5]
	s_waitcnt lgkmcnt(1)
	v_add_f32_e32 v93, v93, v94
	v_cndmask_b32_e64 v64, v64, v91, s[6:7]
	s_waitcnt lgkmcnt(0)
	v_add_f32_e32 v95, v95, v96
	v_cndmask_b32_e64 v64, v64, v93, s[8:9]
	v_add_co_u32_e32 v90, vcc, 0x12500000, v78
	v_cndmask_b32_e64 v64, v64, v95, s[10:11]
	s_nop 0
	v_addc_co_u32_e32 v91, vcc, 0, v79, vcc
	global_store_dword v[90:91], v64, off
.LBB0_163:
	s_or_b64 exec, exec, s[50:51]
	s_waitcnt lgkmcnt(2)
	s_waitcnt lgkmcnt(0)
	s_waitcnt lgkmcnt(0)
	s_waitcnt lgkmcnt(0)
	s_waitcnt vmcnt(1)
	v_lshlrev_b32_e32 v108, 16, v130
	s_waitcnt vmcnt(1)
	v_lshlrev_b32_e32 v102, 16, v134
	v_and_b32_e32 v103, 0xffff0000, v134
	v_lshlrev_b32_e32 v96, 16, v135
	v_and_b32_e32 v97, 0xffff0000, v135
	v_and_b32_e32 v109, 0xffff0000, v130
	v_lshlrev_b32_e32 v110, 16, v131
	v_and_b32_e32 v111, 0xffff0000, v131
	v_lshlrev_b32_e32 v98, 16, v132
	v_and_b32_e32 v99, 0xffff0000, v132
	v_lshlrev_b32_e32 v100, 16, v133
	v_and_b32_e32 v101, 0xffff0000, v133
	v_lshlrev_b32_e32 v104, 16, v128
	v_and_b32_e32 v105, 0xffff0000, v128
	v_lshlrev_b32_e32 v106, 16, v129
	v_and_b32_e32 v107, 0xffff0000, v129
	v_pk_mul_f32 v[90:91], v[10:11], v[96:97]
	v_pk_mul_f32 v[92:93], v[8:9], v[102:103]
	v_pk_mul_f32 v[94:95], v[2:3], v[110:111]
	v_pk_mul_f32 v[112:113], v[0:1], v[108:109]
	v_pk_fma_f32 v[92:93], v[12:13], v[98:99], v[92:93]
	v_pk_fma_f32 v[90:91], v[14:15], v[100:101], v[90:91]
	v_pk_fma_f32 v[112:113], v[4:5], v[104:105], v[112:113]
	v_pk_fma_f32 v[94:95], v[6:7], v[106:107], v[94:95]
	v_pk_add_f32 v[92:93], v[92:93], v[112:113]
	v_pk_add_f32 v[90:91], v[90:91], v[94:95]
	v_pk_mul_f32 v[94:95], v[28:29], v[102:103]
	v_pk_mul_f32 v[114:115], v[20:21], v[108:109]
	v_add_f32_e32 v64, v92, v93
	v_pk_mul_f32 v[92:93], v[30:31], v[96:97]
	v_pk_fma_f32 v[94:95], v[16:17], v[98:99], v[94:95]
	v_pk_mul_f32 v[112:113], v[22:23], v[110:111]
	v_pk_fma_f32 v[114:115], v[24:25], v[104:105], v[114:115]
	v_pk_fma_f32 v[92:93], v[18:19], v[100:101], v[92:93]
	v_pk_fma_f32 v[112:113], v[26:27], v[106:107], v[112:113]
	v_pk_add_f32 v[94:95], v[94:95], v[114:115]
	v_add_f32_e32 v90, v90, v91
	v_pk_add_f32 v[92:93], v[92:93], v[112:113]
	v_add_f32_e32 v91, v94, v95
	v_pk_mul_f32 v[94:95], v[46:47], v[96:97]
	v_pk_mul_f32 v[112:113], v[44:45], v[102:103]
	v_pk_mul_f32 v[96:97], v[62:63], v[96:97]
	v_pk_mul_f32 v[102:103], v[60:61], v[102:103]
	v_pk_fma_f32 v[112:113], v[32:33], v[98:99], v[112:113]
	v_pk_fma_f32 v[94:95], v[34:35], v[100:101], v[94:95]
	v_pk_mul_f32 v[114:115], v[38:39], v[110:111]
	v_pk_mul_f32 v[116:117], v[36:37], v[108:109]
	v_pk_fma_f32 v[98:99], v[48:49], v[98:99], v[102:103]
	v_pk_fma_f32 v[96:97], v[50:51], v[100:101], v[96:97]
	v_pk_mul_f32 v[100:101], v[54:55], v[110:111]
	v_pk_mul_f32 v[102:103], v[52:53], v[108:109]
	v_pk_fma_f32 v[116:117], v[40:41], v[104:105], v[116:117]
	v_pk_fma_f32 v[114:115], v[42:43], v[106:107], v[114:115]
	v_pk_fma_f32 v[102:103], v[56:57], v[104:105], v[102:103]
	v_pk_fma_f32 v[100:101], v[58:59], v[106:107], v[100:101]
	v_pk_add_f32 v[94:95], v[94:95], v[114:115]
	v_pk_add_f32 v[112:113], v[112:113], v[116:117]
	v_pk_add_f32 v[96:97], v[96:97], v[100:101]
	v_pk_add_f32 v[98:99], v[98:99], v[102:103]
	v_add_f32_e32 v92, v92, v93
	v_add_f32_e32 v93, v112, v113
	v_add_f32_e32 v94, v94, v95
	v_add_f32_e32 v95, v98, v99
	v_add_f32_e32 v96, v96, v97
	v_add_f32_e32 v64, v64, v90
	v_add_f32_e32 v91, v91, v92
	v_add_f32_e32 v93, v93, v94
	v_add_f32_e32 v95, v95, v96
	ds_bpermute_b32 v90, v82, v64
	ds_bpermute_b32 v92, v82, v91
	ds_bpermute_b32 v94, v82, v93
	ds_bpermute_b32 v96, v82, v95
	s_waitcnt lgkmcnt(3)
	v_add_f32_e32 v64, v64, v90
	s_waitcnt lgkmcnt(2)
	v_add_f32_e32 v91, v91, v92
	s_waitcnt lgkmcnt(1)
	v_add_f32_e32 v93, v93, v94
	s_waitcnt lgkmcnt(0)
	v_add_f32_e32 v95, v95, v96
	ds_bpermute_b32 v90, v83, v64
	ds_bpermute_b32 v92, v83, v91
	ds_bpermute_b32 v94, v83, v93
	ds_bpermute_b32 v96, v83, v95
	s_waitcnt lgkmcnt(3)
	v_add_f32_e32 v64, v64, v90
	s_waitcnt lgkmcnt(2)
	v_add_f32_e32 v91, v91, v92
	s_waitcnt lgkmcnt(1)
	v_add_f32_e32 v93, v93, v94
	s_waitcnt lgkmcnt(0)
	v_add_f32_e32 v95, v95, v96
	ds_bpermute_b32 v90, v84, v64
	ds_bpermute_b32 v92, v84, v91
	ds_bpermute_b32 v94, v84, v93
	ds_bpermute_b32 v96, v84, v95
	s_waitcnt lgkmcnt(3)
	v_add_f32_e32 v64, v64, v90
	s_waitcnt lgkmcnt(2)
	v_add_f32_e32 v91, v91, v92
	s_waitcnt lgkmcnt(1)
	v_add_f32_e32 v93, v93, v94
	s_waitcnt lgkmcnt(0)
	v_add_f32_e32 v95, v95, v96
	ds_bpermute_b32 v90, v85, v64
	ds_bpermute_b32 v92, v85, v91
	ds_bpermute_b32 v94, v85, v93
	ds_bpermute_b32 v96, v85, v95
	s_waitcnt lgkmcnt(3)
	v_add_f32_e32 v64, v64, v90
	s_waitcnt lgkmcnt(2)
	v_add_f32_e32 v91, v91, v92
	s_waitcnt lgkmcnt(1)
	v_add_f32_e32 v93, v93, v94
	s_waitcnt lgkmcnt(0)
	v_add_f32_e32 v95, v95, v96
	ds_bpermute_b32 v90, v86, v64
	ds_bpermute_b32 v92, v86, v91
	ds_bpermute_b32 v94, v86, v93
	ds_bpermute_b32 v96, v86, v95
	s_waitcnt lgkmcnt(3)
	v_add_f32_e32 v64, v64, v90
	s_waitcnt lgkmcnt(2)
	v_add_f32_e32 v91, v91, v92
	s_waitcnt lgkmcnt(1)
	v_add_f32_e32 v93, v93, v94
	s_waitcnt lgkmcnt(0)
	v_add_f32_e32 v95, v95, v96
	ds_bpermute_b32 v90, v87, v64
	ds_bpermute_b32 v92, v87, v91
	ds_bpermute_b32 v94, v87, v93
	ds_bpermute_b32 v96, v87, v95
	s_and_saveexec_b64 s[50:51], s[0:1]
	s_cbranch_execz .LBB0_160
	s_waitcnt lgkmcnt(3)
	v_add_f32_e32 v64, v64, v90
	s_waitcnt lgkmcnt(2)
	v_add_f32_e32 v91, v91, v92
	v_cndmask_b32_e64 v64, 0, v64, s[4:5]
	s_waitcnt lgkmcnt(1)
	v_add_f32_e32 v93, v93, v94
	v_cndmask_b32_e64 v64, v64, v91, s[6:7]
	s_waitcnt lgkmcnt(0)
	v_add_f32_e32 v95, v95, v96
	v_cndmask_b32_e64 v64, v64, v93, s[8:9]
	v_add_co_u32_e32 v78, vcc, 0x12500000, v78
	v_cndmask_b32_e64 v64, v64, v95, s[10:11]
	s_nop 0
	v_addc_co_u32_e32 v79, vcc, 0, v79, vcc
	global_store_dword v[78:79], v64, off offset:4
	s_branch .LBB0_160

.LBB0_167:
	s_waitcnt lgkmcnt(3)
	global_load_dwordx4 v[74:77], v[70:71], off offset:-2048
	s_waitcnt lgkmcnt(0)
	global_load_dwordx4 v[90:93], v[70:71], off offset:-2032
	global_load_dwordx4 v[128:131], v[70:71], off
	global_load_dwordx4 v[132:135], v[70:71], off offset:16
	s_waitcnt vmcnt(3) lgkmcnt(1)
	v_lshlrev_b32_e32 v94, 16, v76
	v_and_b32_e32 v95, 0xffff0000, v76
	v_lshlrev_b32_e32 v76, 16, v77
	v_and_b32_e32 v77, 0xffff0000, v77
	s_waitcnt vmcnt(2)
	v_lshlrev_b32_e32 v98, 16, v92
	v_and_b32_e32 v99, 0xffff0000, v92
	v_lshlrev_b32_e32 v92, 16, v93
	v_and_b32_e32 v93, 0xffff0000, v93
	v_lshlrev_b32_e32 v78, 16, v74
	v_and_b32_e32 v79, 0xffff0000, v74
	v_lshlrev_b32_e32 v74, 16, v75
	v_and_b32_e32 v75, 0xffff0000, v75
	s_waitcnt lgkmcnt(0)
	v_lshlrev_b32_e32 v96, 16, v90
	v_and_b32_e32 v97, 0xffff0000, v90
	v_lshlrev_b32_e32 v90, 16, v91
	v_and_b32_e32 v91, 0xffff0000, v91
	v_pk_mul_f32 v[100:101], v[12:13], v[94:95]
	v_pk_mul_f32 v[102:103], v[28:29], v[94:95]
	v_pk_mul_f32 v[104:105], v[44:45], v[94:95]
	v_pk_mul_f32 v[94:95], v[60:61], v[94:95]
	v_pk_mul_f32 v[106:107], v[14:15], v[76:77]
	v_pk_mul_f32 v[108:109], v[30:31], v[76:77]
	v_pk_mul_f32 v[110:111], v[46:47], v[76:77]
	v_pk_mul_f32 v[76:77], v[62:63], v[76:77]
	v_pk_mul_f32 v[112:113], v[4:5], v[98:99]
	v_pk_mul_f32 v[114:115], v[20:21], v[98:99]
	v_pk_mul_f32 v[116:117], v[36:37], v[98:99]
	v_pk_mul_f32 v[98:99], v[52:53], v[98:99]
	v_pk_mul_f32 v[118:119], v[6:7], v[92:93]
	v_pk_mul_f32 v[120:121], v[22:23], v[92:93]
	v_pk_mul_f32 v[122:123], v[38:39], v[92:93]
	v_pk_mul_f32 v[92:93], v[54:55], v[92:93]
	v_pk_fma_f32 v[100:101], v[0:1], v[78:79], v[100:101]
	v_pk_fma_f32 v[102:103], v[16:17], v[78:79], v[102:103]
	v_pk_fma_f32 v[104:105], v[32:33], v[78:79], v[104:105]
	v_pk_fma_f32 v[78:79], v[48:49], v[78:79], v[94:95]
	v_pk_fma_f32 v[94:95], v[2:3], v[74:75], v[106:107]
	v_pk_fma_f32 v[106:107], v[18:19], v[74:75], v[108:109]
	v_pk_fma_f32 v[108:109], v[34:35], v[74:75], v[110:111]
	v_pk_fma_f32 v[74:75], v[50:51], v[74:75], v[76:77]
	v_pk_fma_f32 v[76:77], v[8:9], v[96:97], v[112:113]
	v_pk_fma_f32 v[110:111], v[24:25], v[96:97], v[114:115]
	v_pk_fma_f32 v[112:113], v[40:41], v[96:97], v[116:117]
	v_pk_fma_f32 v[96:97], v[56:57], v[96:97], v[98:99]
	v_pk_fma_f32 v[98:99], v[10:11], v[90:91], v[118:119]
	v_pk_fma_f32 v[114:115], v[26:27], v[90:91], v[120:121]
	v_pk_fma_f32 v[116:117], v[42:43], v[90:91], v[122:123]
	v_pk_fma_f32 v[90:91], v[58:59], v[90:91], v[92:93]
	v_pk_add_f32 v[92:93], v[94:95], v[98:99]
	v_pk_add_f32 v[76:77], v[100:101], v[76:77]
	v_pk_add_f32 v[94:95], v[106:107], v[114:115]
	v_pk_add_f32 v[98:99], v[102:103], v[110:111]
	v_pk_add_f32 v[100:101], v[108:109], v[116:117]
	v_pk_add_f32 v[102:103], v[104:105], v[112:113]
	v_pk_add_f32 v[74:75], v[74:75], v[90:91]
	v_pk_add_f32 v[78:79], v[78:79], v[96:97]
	v_add_f32_e32 v64, v76, v77
	v_add_f32_e32 v76, v92, v93
	v_add_f32_e32 v77, v98, v99
	v_add_f32_e32 v89, v94, v95
	v_add_f32_e32 v90, v102, v103
	v_add_f32_e32 v91, v100, v101
	v_add_f32_e32 v78, v78, v79
	v_add_f32_e32 v74, v74, v75
	v_add_f32_e32 v64, v64, v76
	v_add_f32_e32 v75, v77, v89
	v_add_f32_e32 v76, v90, v91
	v_add_f32_e32 v74, v78, v74
	ds_bpermute_b32 v77, v82, v64
	ds_bpermute_b32 v78, v82, v75
	ds_bpermute_b32 v79, v82, v76
	ds_bpermute_b32 v89, v82, v74
	s_waitcnt lgkmcnt(3)
	v_add_f32_e32 v64, v64, v77
	s_waitcnt lgkmcnt(2)
	v_add_f32_e32 v75, v75, v78
	s_waitcnt lgkmcnt(1)
	v_add_f32_e32 v76, v76, v79
	s_waitcnt lgkmcnt(0)
	v_add_f32_e32 v74, v74, v89
	ds_bpermute_b32 v77, v83, v64
	ds_bpermute_b32 v78, v83, v75
	ds_bpermute_b32 v79, v83, v76
	ds_bpermute_b32 v89, v83, v74
	s_waitcnt lgkmcnt(3)
	v_add_f32_e32 v64, v64, v77
	s_waitcnt lgkmcnt(2)
	v_add_f32_e32 v75, v75, v78
	s_waitcnt lgkmcnt(1)
	v_add_f32_e32 v76, v76, v79
	s_waitcnt lgkmcnt(0)
	v_add_f32_e32 v74, v74, v89
	ds_bpermute_b32 v77, v84, v64
	ds_bpermute_b32 v78, v84, v75
	ds_bpermute_b32 v79, v84, v76
	ds_bpermute_b32 v89, v84, v74
	s_waitcnt lgkmcnt(3)
	v_add_f32_e32 v64, v64, v77
	s_waitcnt lgkmcnt(2)
	v_add_f32_e32 v75, v75, v78
	s_waitcnt lgkmcnt(1)
	v_add_f32_e32 v76, v76, v79
	s_waitcnt lgkmcnt(0)
	v_add_f32_e32 v74, v74, v89
	ds_bpermute_b32 v77, v85, v64
	ds_bpermute_b32 v78, v85, v75
	ds_bpermute_b32 v79, v85, v76
	ds_bpermute_b32 v89, v85, v74
	s_waitcnt lgkmcnt(3)
	v_add_f32_e32 v64, v64, v77
	s_waitcnt lgkmcnt(2)
	v_add_f32_e32 v75, v75, v78
	s_waitcnt lgkmcnt(1)
	v_add_f32_e32 v77, v76, v79
	s_waitcnt lgkmcnt(0)
	v_add_f32_e32 v74, v74, v89
	ds_bpermute_b32 v76, v86, v64
	ds_bpermute_b32 v78, v86, v75
	ds_bpermute_b32 v79, v86, v77
	ds_bpermute_b32 v89, v86, v74
	s_waitcnt lgkmcnt(3)
	v_add_f32_e32 v64, v64, v76
	s_waitcnt lgkmcnt(2)
	v_add_f32_e32 v76, v75, v78
	s_waitcnt lgkmcnt(1)
	v_add_f32_e32 v78, v77, v79
	s_waitcnt lgkmcnt(0)
	v_add_f32_e32 v89, v74, v89
	ds_bpermute_b32 v77, v87, v64
	ds_bpermute_b32 v79, v87, v76
	ds_bpermute_b32 v90, v87, v78
	ds_bpermute_b32 v91, v87, v89
	v_lshl_add_u64 v[74:75], v[72:73], 0, s[46:47]
	s_and_saveexec_b64 s[48:49], s[0:1]
	s_cbranch_execz .LBB0_169
	s_waitcnt lgkmcnt(3)
	v_add_f32_e32 v64, v64, v77
	s_waitcnt lgkmcnt(2)
	v_add_f32_e32 v76, v76, v79
	v_cndmask_b32_e64 v64, 0, v64, s[4:5]
	s_waitcnt lgkmcnt(1)
	v_add_f32_e32 v78, v78, v90
	v_cndmask_b32_e64 v64, v64, v76, s[6:7]
	s_waitcnt lgkmcnt(0)
	v_add_f32_e32 v89, v89, v91
	v_cndmask_b32_e64 v64, v64, v78, s[8:9]
	v_add_co_u32_e32 v76, vcc, 0x12500000, v74
	v_cndmask_b32_e64 v64, v64, v89, s[10:11]
	s_nop 0
	v_addc_co_u32_e32 v77, vcc, 0, v75, vcc
	global_store_dword v[76:77], v64, off
.LBB0_169:
	s_or_b64 exec, exec, s[48:49]
	s_waitcnt lgkmcnt(2)
	s_waitcnt lgkmcnt(0)
	s_waitcnt lgkmcnt(0)
	s_waitcnt lgkmcnt(0)
	s_waitcnt vmcnt(1)
	v_lshlrev_b32_e32 v96, 16, v130
	v_and_b32_e32 v97, 0xffff0000, v130
	v_lshlrev_b32_e32 v78, 16, v131
	v_and_b32_e32 v79, 0xffff0000, v131
	s_waitcnt vmcnt(1)
	v_lshlrev_b32_e32 v100, 16, v134
	v_and_b32_e32 v101, 0xffff0000, v134
	v_lshlrev_b32_e32 v92, 16, v135
	v_and_b32_e32 v93, 0xffff0000, v135
	v_lshlrev_b32_e32 v94, 16, v128
	v_and_b32_e32 v95, 0xffff0000, v128
	v_lshlrev_b32_e32 v76, 16, v129
	v_and_b32_e32 v77, 0xffff0000, v129
	v_lshlrev_b32_e32 v98, 16, v132
	v_and_b32_e32 v99, 0xffff0000, v132
	v_lshlrev_b32_e32 v90, 16, v133
	v_and_b32_e32 v91, 0xffff0000, v133
	v_pk_mul_f32 v[102:103], v[14:15], v[78:79]
	v_pk_mul_f32 v[104:105], v[12:13], v[96:97]
	v_pk_mul_f32 v[106:107], v[6:7], v[92:93]
	v_pk_mul_f32 v[108:109], v[4:5], v[100:101]
	v_pk_mul_f32 v[110:111], v[30:31], v[78:79]
	v_pk_mul_f32 v[112:113], v[28:29], v[96:97]
	v_pk_mul_f32 v[114:115], v[22:23], v[92:93]
	v_pk_mul_f32 v[116:117], v[20:21], v[100:101]
	v_pk_mul_f32 v[118:119], v[46:47], v[78:79]
	v_pk_mul_f32 v[120:121], v[44:45], v[96:97]
	v_pk_mul_f32 v[122:123], v[38:39], v[92:93]
	v_pk_mul_f32 v[124:125], v[36:37], v[100:101]
	v_pk_mul_f32 v[78:79], v[62:63], v[78:79]
	v_pk_mul_f32 v[96:97], v[60:61], v[96:97]
	v_pk_mul_f32 v[92:93], v[54:55], v[92:93]
	v_pk_mul_f32 v[100:101], v[52:53], v[100:101]
	v_pk_fma_f32 v[104:105], v[0:1], v[94:95], v[104:105]
	v_pk_fma_f32 v[102:103], v[2:3], v[76:77], v[102:103]
	v_pk_fma_f32 v[108:109], v[8:9], v[98:99], v[108:109]
	v_pk_fma_f32 v[106:107], v[10:11], v[90:91], v[106:107]
	v_pk_fma_f32 v[112:113], v[16:17], v[94:95], v[112:113]
	v_pk_fma_f32 v[110:111], v[18:19], v[76:77], v[110:111]
	v_pk_fma_f32 v[116:117], v[24:25], v[98:99], v[116:117]
	v_pk_fma_f32 v[114:115], v[26:27], v[90:91], v[114:115]
	v_pk_fma_f32 v[120:121], v[32:33], v[94:95], v[120:121]
	v_pk_fma_f32 v[118:119], v[34:35], v[76:77], v[118:119]
	v_pk_fma_f32 v[124:125], v[40:41], v[98:99], v[124:125]
	v_pk_fma_f32 v[122:123], v[42:43], v[90:91], v[122:123]
	v_pk_fma_f32 v[94:95], v[48:49], v[94:95], v[96:97]
	v_pk_fma_f32 v[76:77], v[50:51], v[76:77], v[78:79]
	v_pk_fma_f32 v[78:79], v[56:57], v[98:99], v[100:101]
	v_pk_fma_f32 v[90:91], v[58:59], v[90:91], v[92:93]
	v_pk_add_f32 v[92:93], v[102:103], v[106:107]
	v_pk_add_f32 v[96:97], v[104:105], v[108:109]
	v_pk_add_f32 v[98:99], v[110:111], v[114:115]
	v_pk_add_f32 v[100:101], v[112:113], v[116:117]
	v_pk_add_f32 v[102:103], v[118:119], v[122:123]
	v_pk_add_f32 v[104:105], v[120:121], v[124:125]
	v_pk_add_f32 v[76:77], v[76:77], v[90:91]
	v_pk_add_f32 v[78:79], v[94:95], v[78:79]
	v_add_f32_e32 v64, v96, v97
	v_add_f32_e32 v89, v92, v93
	v_add_f32_e32 v90, v100, v101
	v_add_f32_e32 v91, v98, v99
	v_add_f32_e32 v92, v104, v105
	v_add_f32_e32 v93, v102, v103
	v_add_f32_e32 v78, v78, v79
	v_add_f32_e32 v76, v76, v77
	v_add_f32_e32 v64, v64, v89
	v_add_f32_e32 v77, v90, v91
	v_add_f32_e32 v79, v92, v93
	v_add_f32_e32 v76, v78, v76
	ds_bpermute_b32 v78, v82, v64
	ds_bpermute_b32 v89, v82, v77
	ds_bpermute_b32 v90, v82, v79
	ds_bpermute_b32 v91, v82, v76
	s_waitcnt lgkmcnt(3)
	v_add_f32_e32 v64, v64, v78
	s_waitcnt lgkmcnt(2)
	v_add_f32_e32 v77, v77, v89
	s_waitcnt lgkmcnt(1)
	v_add_f32_e32 v78, v79, v90
	s_waitcnt lgkmcnt(0)
	v_add_f32_e32 v76, v76, v91
	ds_bpermute_b32 v79, v83, v64
	ds_bpermute_b32 v89, v83, v77
	ds_bpermute_b32 v90, v83, v78
	ds_bpermute_b32 v91, v83, v76
	s_waitcnt lgkmcnt(3)
	v_add_f32_e32 v64, v64, v79
	s_waitcnt lgkmcnt(2)
	v_add_f32_e32 v77, v77, v89
	s_waitcnt lgkmcnt(1)
	v_add_f32_e32 v78, v78, v90
	s_waitcnt lgkmcnt(0)
	v_add_f32_e32 v76, v76, v91
	ds_bpermute_b32 v79, v84, v64
	ds_bpermute_b32 v89, v84, v77
	ds_bpermute_b32 v90, v84, v78
	ds_bpermute_b32 v91, v84, v76
	s_waitcnt lgkmcnt(3)
	v_add_f32_e32 v64, v64, v79
	s_waitcnt lgkmcnt(2)
	v_add_f32_e32 v77, v77, v89
	s_waitcnt lgkmcnt(1)
	v_add_f32_e32 v78, v78, v90
	s_waitcnt lgkmcnt(0)
	v_add_f32_e32 v76, v76, v91
	ds_bpermute_b32 v79, v85, v64
	ds_bpermute_b32 v89, v85, v77
	ds_bpermute_b32 v90, v85, v78
	ds_bpermute_b32 v91, v85, v76
	s_waitcnt lgkmcnt(3)
	v_add_f32_e32 v64, v64, v79
	s_waitcnt lgkmcnt(2)
	v_add_f32_e32 v77, v77, v89
	s_waitcnt lgkmcnt(1)
	v_add_f32_e32 v78, v78, v90
	s_waitcnt lgkmcnt(0)
	v_add_f32_e32 v79, v76, v91
	ds_bpermute_b32 v76, v86, v64
	ds_bpermute_b32 v89, v86, v77
	ds_bpermute_b32 v90, v86, v78
	ds_bpermute_b32 v91, v86, v79
	s_waitcnt lgkmcnt(3)
	v_add_f32_e32 v64, v64, v76
	s_waitcnt lgkmcnt(2)
	v_add_f32_e32 v76, v77, v89
	s_waitcnt lgkmcnt(1)
	v_add_f32_e32 v78, v78, v90
	s_waitcnt lgkmcnt(0)
	v_add_f32_e32 v89, v79, v91
	ds_bpermute_b32 v77, v87, v64
	ds_bpermute_b32 v79, v87, v76
	ds_bpermute_b32 v90, v87, v78
	ds_bpermute_b32 v91, v87, v89
	s_and_saveexec_b64 s[48:49], s[0:1]
	s_cbranch_execz .LBB0_166
	s_waitcnt lgkmcnt(3)
	v_add_f32_e32 v64, v64, v77
	s_waitcnt lgkmcnt(2)
	v_add_f32_e32 v76, v76, v79
	v_cndmask_b32_e64 v64, 0, v64, s[4:5]
	s_waitcnt lgkmcnt(1)
	v_add_f32_e32 v78, v78, v90
	v_cndmask_b32_e64 v64, v64, v76, s[6:7]
	s_waitcnt lgkmcnt(0)
	v_add_f32_e32 v89, v89, v91
	v_cndmask_b32_e64 v64, v64, v78, s[8:9]
	v_add_co_u32_e32 v74, vcc, 0x12500000, v74
	v_cndmask_b32_e64 v64, v64, v89, s[10:11]
	s_nop 0
	v_addc_co_u32_e32 v75, vcc, 0, v75, vcc
	global_store_dword v[74:75], v64, off offset:4
	s_branch .LBB0_166
